# kv up-projection epilogue: the V-half waves store their values before the workgroup barrier (while the K-half waves do the first pass); only the shared rope key waits for the exchange
# baseline (speedup 1.0000x reference)
.LBB0_953:
	s_cmp_lt_i32 s66, 3
	s_mov_b64 s[0:1], -1
	s_cbranch_scc1 .LBB0_1091
	s_cmp_gt_i32 s66, 3
	s_cbranch_scc0 .LBB0_1088
	s_waitcnt lgkmcnt(0)
	v_and_b32_e32 v80, 15, v192
	v_ashrrev_i32_e32 v82, 2, v192
	s_movk_i32 s0, 0xffc0
	v_and_or_b32 v145, v82, s0, v80
	v_bfe_u32 v144, v192, 6, 2
	v_bfe_u32 v146, v192, 4, 2
	v_add_u32_e32 v148, s30, v145
	v_ashrrev_i32_e32 v149, 31, v148
	v_lshl_add_u64 v[82:83], v[148:149], 2, s[90:91]
	s_mov_b64 s[10:11], 0xa0000
	s_nop 0
	v_lshl_add_u64 v[140:141], v[82:83], 0, s[10:11]
	s_mov_b64 s[10:11], 0x100000
	s_nop 0
	v_lshl_add_u64 v[142:143], v[82:83], 0, s[10:11]
	global_load_dword v204, v[140:141], off
	global_load_dword v205, v[140:141], off offset:64
	global_load_dword v206, v[140:141], off offset:128
	global_load_dword v207, v[140:141], off offset:192
	global_load_dword v208, v[140:141], off offset:512
	global_load_dword v209, v[140:141], off offset:576
	global_load_dword v210, v[140:141], off offset:640
	global_load_dword v211, v[140:141], off offset:704
	global_load_dword v132, v[142:143], off
	global_load_dword v133, v[142:143], off offset:64
	global_load_dword v134, v[142:143], off offset:128
	global_load_dword v135, v[142:143], off offset:192
	global_load_dword v136, v[142:143], off offset:512
	global_load_dword v137, v[142:143], off offset:576
	global_load_dword v138, v[142:143], off offset:640
	global_load_dword v139, v[142:143], off offset:704
	v_cmp_eq_u32_e64 s[40:41], 0, v146
	v_readfirstlane_b32 s37, v144
	v_ashrrev_i32_e32 v150, 9, v148
	v_and_b32_e32 v150, -8, v150
	s_ashr_i32 s7, s6, 7
	v_add_u32_e32 v150, s7, v150
	v_lshlrev_b32_e32 v150, 12, v150
	v_and_b32_e32 v151, 0xfff, v148
	v_or_b32_e32 v150, v150, v151
	v_mul_u32_u24_e32 v150, 0xc0, v150
	v_lshlrev_b32_e32 v151, 4, v146
	v_add_u32_e32 v150, v150, v151
	v_mov_b32_e32 v151, v81
	v_lshl_add_u64 v[150:151], v[150:151], 0, s[58:59]
	v_lshl_add_u32 v147, v145, 4, 16
	s_cmp_lt_u32 s37, 2
	s_cbranch_scc1 .Lkv_p1
	v_readlane_b32 s42, v253, 12
	v_lshlrev_b64 v[244:245], 6, v[148:149]
	v_readlane_b32 s43, v253, 13
	v_lshlrev_b32_e32 v246, 4, v146
	v_mov_b32_e32 v247, v81
	v_lshl_add_u64 v[244:245], s[42:43], 0, v[244:245]
	v_lshl_add_u64 v[244:245], v[244:245], 0, v[246:247]
	s_mov_b64 s[10:11], 0x2000
	s_nop 0
	v_lshl_add_u64 v[246:247], v[244:245], 0, s[10:11]
	global_load_dwordx4 v[160:163], v[244:245], off
	global_load_dwordx4 v[164:167], v[244:245], off offset:1024
	global_load_dwordx4 v[168:171], v[244:245], off offset:2048
	global_load_dwordx4 v[172:175], v[244:245], off offset:3072
	global_load_dwordx4 v[176:179], v[246:247], off
	global_load_dwordx4 v[180:183], v[246:247], off offset:1024
	global_load_dwordx4 v[184:187], v[246:247], off offset:2048
	global_load_dwordx4 v[188:191], v[246:247], off offset:3072
	v_readlane_b32 s10, v252, 22
	v_lshlrev_b64 v[248:249], 11, v[148:149]
	v_readlane_b32 s11, v252, 23
	v_lshl_add_u32 v250, v144, 5, s6
	v_lshl_add_u32 v250, v146, 3, v250
	v_lshlrev_b32_e32 v250, 1, v250
	v_lshl_add_u64 v[248:249], s[10:11], 0, v[248:249]
	v_mov_b32_e32 v83, v81
	v_mov_b32_e32 v82, v250
	v_lshl_add_u64 v[248:249], v[248:249], 0, v[82:83]
	s_sub_u32 s7, s37, 2
	s_mul_i32 s10, s7, 0xc0000
	s_add_u32 s10, s10, 0x80
	s_mov_b32 s11, 0
	v_lshl_add_u64 v[150:151], v[150:151], 0, s[10:11]
	s_lshl_b32 s7, s7, 3
	v_add_u32_e32 v147, s7, v147
	s_waitcnt vmcnt(16)
	v_fmamk_f32 v204, v204, 0x3b800000, v194
	v_fmamk_f32 v205, v205, 0x3b800000, v194
	v_fmamk_f32 v206, v206, 0x3b800000, v194
	v_fmamk_f32 v207, v207, 0x3b800000, v194
	v_fmamk_f32 v208, v208, 0x3b800000, v194
	v_fmamk_f32 v209, v209, 0x3b800000, v194
	v_fmamk_f32 v210, v210, 0x3b800000, v194
	v_fmamk_f32 v211, v211, 0x3b800000, v194
	v_rsq_f32_e32 v204, v204
	v_rsq_f32_e32 v205, v205
	v_rsq_f32_e32 v206, v206
	v_rsq_f32_e32 v207, v207
	v_rsq_f32_e32 v208, v208
	v_rsq_f32_e32 v209, v209
	v_rsq_f32_e32 v210, v210
	v_rsq_f32_e32 v211, v211
	v_mov_b32_e32 v80, v204
	v_pk_mul_f32 v[128:129], v[128:129], v[80:81] op_sel_hi:[1,0]
	v_pk_mul_f32 v[130:131], v[130:131], v[80:81] op_sel_hi:[1,0]
	v_pk_mul_f32 v[124:125], v[124:125], v[80:81] op_sel_hi:[1,0]
	v_pk_mul_f32 v[126:127], v[126:127], v[80:81] op_sel_hi:[1,0]
	v_cvt_pk_bf16_f32 v128, v128, v129
	v_cvt_pk_bf16_f32 v129, v130, v131
	v_cvt_pk_bf16_f32 v130, v124, v125
	v_cvt_pk_bf16_f32 v131, v126, v127
	global_store_dwordx4 v[248:249], v[128:131], off
	v_pk_mul_f32 v[120:121], v[120:121], v[80:81] op_sel_hi:[1,0]
	v_pk_mul_f32 v[122:123], v[122:123], v[80:81] op_sel_hi:[1,0]
	v_pk_mul_f32 v[116:117], v[116:117], v[80:81] op_sel_hi:[1,0]
	v_pk_mul_f32 v[118:119], v[118:119], v[80:81] op_sel_hi:[1,0]
	v_cvt_pk_bf16_f32 v120, v120, v121
	v_cvt_pk_bf16_f32 v121, v122, v123
	v_cvt_pk_bf16_f32 v122, v116, v117
	v_cvt_pk_bf16_f32 v123, v118, v119
	global_store_dwordx4 v[248:249], v[120:123], off offset:256
	s_mov_b64 vcc, 0x8000
	s_nop 0
	v_lshl_add_u64 v[248:249], v[248:249], 0, vcc
	v_mov_b32_e32 v80, v205
	v_pk_mul_f32 v[112:113], v[112:113], v[80:81] op_sel_hi:[1,0]
	v_pk_mul_f32 v[114:115], v[114:115], v[80:81] op_sel_hi:[1,0]
	v_pk_mul_f32 v[108:109], v[108:109], v[80:81] op_sel_hi:[1,0]
	v_pk_mul_f32 v[110:111], v[110:111], v[80:81] op_sel_hi:[1,0]
	v_cvt_pk_bf16_f32 v112, v112, v113
	v_cvt_pk_bf16_f32 v113, v114, v115
	v_cvt_pk_bf16_f32 v114, v108, v109
	v_cvt_pk_bf16_f32 v115, v110, v111
	global_store_dwordx4 v[248:249], v[112:115], off
	v_pk_mul_f32 v[104:105], v[104:105], v[80:81] op_sel_hi:[1,0]
	v_pk_mul_f32 v[106:107], v[106:107], v[80:81] op_sel_hi:[1,0]
	v_pk_mul_f32 v[100:101], v[100:101], v[80:81] op_sel_hi:[1,0]
	v_pk_mul_f32 v[102:103], v[102:103], v[80:81] op_sel_hi:[1,0]
	v_cvt_pk_bf16_f32 v104, v104, v105
	v_cvt_pk_bf16_f32 v105, v106, v107
	v_cvt_pk_bf16_f32 v106, v100, v101
	v_cvt_pk_bf16_f32 v107, v102, v103
	global_store_dwordx4 v[248:249], v[104:107], off offset:256
	s_mov_b64 vcc, 0x8000
	s_nop 0
	v_lshl_add_u64 v[248:249], v[248:249], 0, vcc
	v_mov_b32_e32 v80, v206
	v_pk_mul_f32 v[96:97], v[96:97], v[80:81] op_sel_hi:[1,0]
	v_pk_mul_f32 v[98:99], v[98:99], v[80:81] op_sel_hi:[1,0]
	v_pk_mul_f32 v[92:93], v[92:93], v[80:81] op_sel_hi:[1,0]
	v_pk_mul_f32 v[94:95], v[94:95], v[80:81] op_sel_hi:[1,0]
	v_cvt_pk_bf16_f32 v96, v96, v97
	v_cvt_pk_bf16_f32 v97, v98, v99
	v_cvt_pk_bf16_f32 v98, v92, v93
	v_cvt_pk_bf16_f32 v99, v94, v95
	global_store_dwordx4 v[248:249], v[96:99], off
	v_pk_mul_f32 v[88:89], v[88:89], v[80:81] op_sel_hi:[1,0]
	v_pk_mul_f32 v[90:91], v[90:91], v[80:81] op_sel_hi:[1,0]
	v_pk_mul_f32 v[84:85], v[84:85], v[80:81] op_sel_hi:[1,0]
	v_pk_mul_f32 v[86:87], v[86:87], v[80:81] op_sel_hi:[1,0]
	v_cvt_pk_bf16_f32 v88, v88, v89
	v_cvt_pk_bf16_f32 v89, v90, v91
	v_cvt_pk_bf16_f32 v90, v84, v85
	v_cvt_pk_bf16_f32 v91, v86, v87
	global_store_dwordx4 v[248:249], v[88:91], off offset:256
	s_mov_b64 vcc, 0x8000
	s_nop 0
	v_lshl_add_u64 v[248:249], v[248:249], 0, vcc
	v_mov_b32_e32 v80, v207
	v_pk_mul_f32 v[76:77], v[76:77], v[80:81] op_sel_hi:[1,0]
	v_pk_mul_f32 v[78:79], v[78:79], v[80:81] op_sel_hi:[1,0]
	v_pk_mul_f32 v[72:73], v[72:73], v[80:81] op_sel_hi:[1,0]
	v_pk_mul_f32 v[74:75], v[74:75], v[80:81] op_sel_hi:[1,0]
	v_cvt_pk_bf16_f32 v76, v76, v77
	v_cvt_pk_bf16_f32 v77, v78, v79
	v_cvt_pk_bf16_f32 v78, v72, v73
	v_cvt_pk_bf16_f32 v79, v74, v75
	global_store_dwordx4 v[248:249], v[76:79], off
	v_pk_mul_f32 v[68:69], v[68:69], v[80:81] op_sel_hi:[1,0]
	v_pk_mul_f32 v[70:71], v[70:71], v[80:81] op_sel_hi:[1,0]
	v_pk_mul_f32 v[64:65], v[64:65], v[80:81] op_sel_hi:[1,0]
	v_pk_mul_f32 v[66:67], v[66:67], v[80:81] op_sel_hi:[1,0]
	v_cvt_pk_bf16_f32 v68, v68, v69
	v_cvt_pk_bf16_f32 v69, v70, v71
	v_cvt_pk_bf16_f32 v70, v64, v65
	v_cvt_pk_bf16_f32 v71, v66, v67
	global_store_dwordx4 v[248:249], v[68:71], off offset:256
	s_mov_b64 vcc, 0x28000
	s_nop 0
	v_lshl_add_u64 v[248:249], v[248:249], 0, vcc
	v_mov_b32_e32 v80, v208
	v_pk_mul_f32 v[60:61], v[60:61], v[80:81] op_sel_hi:[1,0]
	v_pk_mul_f32 v[62:63], v[62:63], v[80:81] op_sel_hi:[1,0]
	v_pk_mul_f32 v[56:57], v[56:57], v[80:81] op_sel_hi:[1,0]
	v_pk_mul_f32 v[58:59], v[58:59], v[80:81] op_sel_hi:[1,0]
	v_cvt_pk_bf16_f32 v60, v60, v61
	v_cvt_pk_bf16_f32 v61, v62, v63
	v_cvt_pk_bf16_f32 v62, v56, v57
	v_cvt_pk_bf16_f32 v63, v58, v59
	global_store_dwordx4 v[248:249], v[60:63], off
	v_pk_mul_f32 v[52:53], v[52:53], v[80:81] op_sel_hi:[1,0]
	v_pk_mul_f32 v[54:55], v[54:55], v[80:81] op_sel_hi:[1,0]
	v_pk_mul_f32 v[48:49], v[48:49], v[80:81] op_sel_hi:[1,0]
	v_pk_mul_f32 v[50:51], v[50:51], v[80:81] op_sel_hi:[1,0]
	v_cvt_pk_bf16_f32 v52, v52, v53
	v_cvt_pk_bf16_f32 v53, v54, v55
	v_cvt_pk_bf16_f32 v54, v48, v49
	v_cvt_pk_bf16_f32 v55, v50, v51
	global_store_dwordx4 v[248:249], v[52:55], off offset:256
	s_mov_b64 vcc, 0x8000
	s_nop 0
	v_lshl_add_u64 v[248:249], v[248:249], 0, vcc
	v_mov_b32_e32 v80, v209
	v_pk_mul_f32 v[44:45], v[44:45], v[80:81] op_sel_hi:[1,0]
	v_pk_mul_f32 v[46:47], v[46:47], v[80:81] op_sel_hi:[1,0]
	v_pk_mul_f32 v[40:41], v[40:41], v[80:81] op_sel_hi:[1,0]
	v_pk_mul_f32 v[42:43], v[42:43], v[80:81] op_sel_hi:[1,0]
	v_cvt_pk_bf16_f32 v44, v44, v45
	v_cvt_pk_bf16_f32 v45, v46, v47
	v_cvt_pk_bf16_f32 v46, v40, v41
	v_cvt_pk_bf16_f32 v47, v42, v43
	global_store_dwordx4 v[248:249], v[44:47], off
	v_pk_mul_f32 v[36:37], v[36:37], v[80:81] op_sel_hi:[1,0]
	v_pk_mul_f32 v[38:39], v[38:39], v[80:81] op_sel_hi:[1,0]
	v_pk_mul_f32 v[32:33], v[32:33], v[80:81] op_sel_hi:[1,0]
	v_pk_mul_f32 v[34:35], v[34:35], v[80:81] op_sel_hi:[1,0]
	v_cvt_pk_bf16_f32 v36, v36, v37
	v_cvt_pk_bf16_f32 v37, v38, v39
	v_cvt_pk_bf16_f32 v38, v32, v33
	v_cvt_pk_bf16_f32 v39, v34, v35
	global_store_dwordx4 v[248:249], v[36:39], off offset:256
	s_mov_b64 vcc, 0x8000
	s_nop 0
	v_lshl_add_u64 v[248:249], v[248:249], 0, vcc
	v_mov_b32_e32 v80, v210
	v_pk_mul_f32 v[28:29], v[28:29], v[80:81] op_sel_hi:[1,0]
	v_pk_mul_f32 v[30:31], v[30:31], v[80:81] op_sel_hi:[1,0]
	v_pk_mul_f32 v[24:25], v[24:25], v[80:81] op_sel_hi:[1,0]
	v_pk_mul_f32 v[26:27], v[26:27], v[80:81] op_sel_hi:[1,0]
	v_cvt_pk_bf16_f32 v28, v28, v29
	v_cvt_pk_bf16_f32 v29, v30, v31
	v_cvt_pk_bf16_f32 v30, v24, v25
	v_cvt_pk_bf16_f32 v31, v26, v27
	global_store_dwordx4 v[248:249], v[28:31], off
	v_pk_mul_f32 v[20:21], v[20:21], v[80:81] op_sel_hi:[1,0]
	v_pk_mul_f32 v[22:23], v[22:23], v[80:81] op_sel_hi:[1,0]
	v_pk_mul_f32 v[16:17], v[16:17], v[80:81] op_sel_hi:[1,0]
	v_pk_mul_f32 v[18:19], v[18:19], v[80:81] op_sel_hi:[1,0]
	v_cvt_pk_bf16_f32 v20, v20, v21
	v_cvt_pk_bf16_f32 v21, v22, v23
	v_cvt_pk_bf16_f32 v22, v16, v17
	v_cvt_pk_bf16_f32 v23, v18, v19
	global_store_dwordx4 v[248:249], v[20:23], off offset:256
	s_mov_b64 vcc, 0x8000
	s_nop 0
	v_lshl_add_u64 v[248:249], v[248:249], 0, vcc
	v_mov_b32_e32 v80, v211
	v_pk_mul_f32 v[12:13], v[12:13], v[80:81] op_sel_hi:[1,0]
	v_pk_mul_f32 v[14:15], v[14:15], v[80:81] op_sel_hi:[1,0]
	v_pk_mul_f32 v[8:9], v[8:9], v[80:81] op_sel_hi:[1,0]
	v_pk_mul_f32 v[10:11], v[10:11], v[80:81] op_sel_hi:[1,0]
	v_cvt_pk_bf16_f32 v12, v12, v13
	v_cvt_pk_bf16_f32 v13, v14, v15
	v_cvt_pk_bf16_f32 v14, v8, v9
	v_cvt_pk_bf16_f32 v15, v10, v11
	global_store_dwordx4 v[248:249], v[12:15], off
	v_pk_mul_f32 v[4:5], v[4:5], v[80:81] op_sel_hi:[1,0]
	v_pk_mul_f32 v[6:7], v[6:7], v[80:81] op_sel_hi:[1,0]
	v_pk_mul_f32 v[0:1], v[0:1], v[80:81] op_sel_hi:[1,0]
	v_pk_mul_f32 v[2:3], v[2:3], v[80:81] op_sel_hi:[1,0]
	v_cvt_pk_bf16_f32 v4, v4, v5
	v_cvt_pk_bf16_f32 v5, v6, v7
	v_cvt_pk_bf16_f32 v6, v0, v1
	v_cvt_pk_bf16_f32 v7, v2, v3
	global_store_dwordx4 v[248:249], v[4:7], off offset:256
	s_waitcnt vmcnt(16)
	s_branch .Lkv_bar
.Lkv_p1:
	v_lshl_add_u32 v248, v144, 2, v147
	s_waitcnt vmcnt(8)
	v_fmamk_f32 v204, v204, 0x3b800000, v194
	v_fmamk_f32 v205, v205, 0x3b800000, v194
	v_fmamk_f32 v206, v206, 0x3b800000, v194
	v_fmamk_f32 v207, v207, 0x3b800000, v194
	v_fmamk_f32 v208, v208, 0x3b800000, v194
	v_fmamk_f32 v209, v209, 0x3b800000, v194
	v_fmamk_f32 v210, v210, 0x3b800000, v194
	v_fmamk_f32 v211, v211, 0x3b800000, v194
	v_rsq_f32_e32 v204, v204
	v_rsq_f32_e32 v205, v205
	v_rsq_f32_e32 v206, v206
	v_rsq_f32_e32 v207, v207
	v_rsq_f32_e32 v208, v208
	v_rsq_f32_e32 v209, v209
	v_rsq_f32_e32 v210, v210
	v_rsq_f32_e32 v211, v211
	v_mul_f32_e32 v250, v204, v204
	v_pk_mul_f32 v[244:245], v[128:129], v[128:129]
	v_pk_fma_f32 v[244:245], v[130:131], v[130:131], v[244:245]
	v_pk_fma_f32 v[244:245], v[124:125], v[124:125], v[244:245]
	v_pk_fma_f32 v[244:245], v[126:127], v[126:127], v[244:245]
	v_add_f32_e32 v246, v244, v245
	v_mul_f32_e32 v246, v246, v250
	v_mov_b32_e32 v247, v246
	s_nop 1
	v_permlane32_swap_b32 v247, v246
	s_nop 1
	v_add_f32_e32 v246, v246, v247
	v_mov_b32_e32 v247, v246
	s_nop 1
	v_permlane16_swap_b32 v247, v246
	s_nop 1
	v_add_f32_e32 v246, v246, v247
	s_mov_b64 exec, s[40:41]
	ds_write_b32 v248, v246 offset:32768
	s_mov_b64 exec, -1
	v_pk_mul_f32 v[244:245], v[120:121], v[120:121]
	v_pk_fma_f32 v[244:245], v[122:123], v[122:123], v[244:245]
	v_pk_fma_f32 v[244:245], v[116:117], v[116:117], v[244:245]
	v_pk_fma_f32 v[244:245], v[118:119], v[118:119], v[244:245]
	v_add_f32_e32 v246, v244, v245
	v_mul_f32_e32 v246, v246, v250
	v_mov_b32_e32 v247, v246
	s_nop 1
	v_permlane32_swap_b32 v247, v246
	s_nop 1
	v_add_f32_e32 v246, v246, v247
	v_mov_b32_e32 v247, v246
	s_nop 1
	v_permlane16_swap_b32 v247, v246
	s_nop 1
	v_add_f32_e32 v246, v246, v247
	s_mov_b64 exec, s[40:41]
	ds_write_b32 v248, v246 offset:32776
	s_mov_b64 exec, -1
	v_mul_f32_e32 v250, v205, v205
	v_pk_mul_f32 v[244:245], v[112:113], v[112:113]
	v_pk_fma_f32 v[244:245], v[114:115], v[114:115], v[244:245]
	v_pk_fma_f32 v[244:245], v[108:109], v[108:109], v[244:245]
	v_pk_fma_f32 v[244:245], v[110:111], v[110:111], v[244:245]
	v_add_f32_e32 v246, v244, v245
	v_mul_f32_e32 v246, v246, v250
	v_mov_b32_e32 v247, v246
	s_nop 1
	v_permlane32_swap_b32 v247, v246
	s_nop 1
	v_add_f32_e32 v246, v246, v247
	v_mov_b32_e32 v247, v246
	s_nop 1
	v_permlane16_swap_b32 v247, v246
	s_nop 1
	v_add_f32_e32 v246, v246, v247
	s_mov_b64 exec, s[40:41]
	ds_write_b32 v248, v246 offset:33024
	s_mov_b64 exec, -1
	v_pk_mul_f32 v[244:245], v[104:105], v[104:105]
	v_pk_fma_f32 v[244:245], v[106:107], v[106:107], v[244:245]
	v_pk_fma_f32 v[244:245], v[100:101], v[100:101], v[244:245]
	v_pk_fma_f32 v[244:245], v[102:103], v[102:103], v[244:245]
	v_add_f32_e32 v246, v244, v245
	v_mul_f32_e32 v246, v246, v250
	v_mov_b32_e32 v247, v246
	s_nop 1
	v_permlane32_swap_b32 v247, v246
	s_nop 1
	v_add_f32_e32 v246, v246, v247
	v_mov_b32_e32 v247, v246
	s_nop 1
	v_permlane16_swap_b32 v247, v246
	s_nop 1
	v_add_f32_e32 v246, v246, v247
	s_mov_b64 exec, s[40:41]
	ds_write_b32 v248, v246 offset:33032
	s_mov_b64 exec, -1
	v_mul_f32_e32 v250, v206, v206
	v_pk_mul_f32 v[244:245], v[96:97], v[96:97]
	v_pk_fma_f32 v[244:245], v[98:99], v[98:99], v[244:245]
	v_pk_fma_f32 v[244:245], v[92:93], v[92:93], v[244:245]
	v_pk_fma_f32 v[244:245], v[94:95], v[94:95], v[244:245]
	v_add_f32_e32 v246, v244, v245
	v_mul_f32_e32 v246, v246, v250
	v_mov_b32_e32 v247, v246
	s_nop 1
	v_permlane32_swap_b32 v247, v246
	s_nop 1
	v_add_f32_e32 v246, v246, v247
	v_mov_b32_e32 v247, v246
	s_nop 1
	v_permlane16_swap_b32 v247, v246
	s_nop 1
	v_add_f32_e32 v246, v246, v247
	s_mov_b64 exec, s[40:41]
	ds_write_b32 v248, v246 offset:33280
	s_mov_b64 exec, -1
	v_pk_mul_f32 v[244:245], v[88:89], v[88:89]
	v_pk_fma_f32 v[244:245], v[90:91], v[90:91], v[244:245]
	v_pk_fma_f32 v[244:245], v[84:85], v[84:85], v[244:245]
	v_pk_fma_f32 v[244:245], v[86:87], v[86:87], v[244:245]
	v_add_f32_e32 v246, v244, v245
	v_mul_f32_e32 v246, v246, v250
	v_mov_b32_e32 v247, v246
	s_nop 1
	v_permlane32_swap_b32 v247, v246
	s_nop 1
	v_add_f32_e32 v246, v246, v247
	v_mov_b32_e32 v247, v246
	s_nop 1
	v_permlane16_swap_b32 v247, v246
	s_nop 1
	v_add_f32_e32 v246, v246, v247
	s_mov_b64 exec, s[40:41]
	ds_write_b32 v248, v246 offset:33288
	s_mov_b64 exec, -1
	v_mul_f32_e32 v250, v207, v207
	v_pk_mul_f32 v[244:245], v[76:77], v[76:77]
	v_pk_fma_f32 v[244:245], v[78:79], v[78:79], v[244:245]
	v_pk_fma_f32 v[244:245], v[72:73], v[72:73], v[244:245]
	v_pk_fma_f32 v[244:245], v[74:75], v[74:75], v[244:245]
	v_add_f32_e32 v246, v244, v245
	v_mul_f32_e32 v246, v246, v250
	v_mov_b32_e32 v247, v246
	s_nop 1
	v_permlane32_swap_b32 v247, v246
	s_nop 1
	v_add_f32_e32 v246, v246, v247
	v_mov_b32_e32 v247, v246
	s_nop 1
	v_permlane16_swap_b32 v247, v246
	s_nop 1
	v_add_f32_e32 v246, v246, v247
	s_mov_b64 exec, s[40:41]
	ds_write_b32 v248, v246 offset:33536
	s_mov_b64 exec, -1
	v_pk_mul_f32 v[244:245], v[68:69], v[68:69]
	v_pk_fma_f32 v[244:245], v[70:71], v[70:71], v[244:245]
	v_pk_fma_f32 v[244:245], v[64:65], v[64:65], v[244:245]
	v_pk_fma_f32 v[244:245], v[66:67], v[66:67], v[244:245]
	v_add_f32_e32 v246, v244, v245
	v_mul_f32_e32 v246, v246, v250
	v_mov_b32_e32 v247, v246
	s_nop 1
	v_permlane32_swap_b32 v247, v246
	s_nop 1
	v_add_f32_e32 v246, v246, v247
	v_mov_b32_e32 v247, v246
	s_nop 1
	v_permlane16_swap_b32 v247, v246
	s_nop 1
	v_add_f32_e32 v246, v246, v247
	s_mov_b64 exec, s[40:41]
	ds_write_b32 v248, v246 offset:33544
	s_mov_b64 exec, -1
	v_mul_f32_e32 v250, v208, v208
	v_pk_mul_f32 v[244:245], v[60:61], v[60:61]
	v_pk_fma_f32 v[244:245], v[62:63], v[62:63], v[244:245]
	v_pk_fma_f32 v[244:245], v[56:57], v[56:57], v[244:245]
	v_pk_fma_f32 v[244:245], v[58:59], v[58:59], v[244:245]
	v_add_f32_e32 v246, v244, v245
	v_mul_f32_e32 v246, v246, v250
	v_mov_b32_e32 v247, v246
	s_nop 1
	v_permlane32_swap_b32 v247, v246
	s_nop 1
	v_add_f32_e32 v246, v246, v247
	v_mov_b32_e32 v247, v246
	s_nop 1
	v_permlane16_swap_b32 v247, v246
	s_nop 1
	v_add_f32_e32 v246, v246, v247
	s_mov_b64 exec, s[40:41]
	ds_write_b32 v248, v246 offset:34816
	s_mov_b64 exec, -1
	v_pk_mul_f32 v[244:245], v[52:53], v[52:53]
	v_pk_fma_f32 v[244:245], v[54:55], v[54:55], v[244:245]
	v_pk_fma_f32 v[244:245], v[48:49], v[48:49], v[244:245]
	v_pk_fma_f32 v[244:245], v[50:51], v[50:51], v[244:245]
	v_add_f32_e32 v246, v244, v245
	v_mul_f32_e32 v246, v246, v250
	v_mov_b32_e32 v247, v246
	s_nop 1
	v_permlane32_swap_b32 v247, v246
	s_nop 1
	v_add_f32_e32 v246, v246, v247
	v_mov_b32_e32 v247, v246
	s_nop 1
	v_permlane16_swap_b32 v247, v246
	s_nop 1
	v_add_f32_e32 v246, v246, v247
	s_mov_b64 exec, s[40:41]
	ds_write_b32 v248, v246 offset:34824
	s_mov_b64 exec, -1
	v_mul_f32_e32 v250, v209, v209
	v_pk_mul_f32 v[244:245], v[44:45], v[44:45]
	v_pk_fma_f32 v[244:245], v[46:47], v[46:47], v[244:245]
	v_pk_fma_f32 v[244:245], v[40:41], v[40:41], v[244:245]
	v_pk_fma_f32 v[244:245], v[42:43], v[42:43], v[244:245]
	v_add_f32_e32 v246, v244, v245
	v_mul_f32_e32 v246, v246, v250
	v_mov_b32_e32 v247, v246
	s_nop 1
	v_permlane32_swap_b32 v247, v246
	s_nop 1
	v_add_f32_e32 v246, v246, v247
	v_mov_b32_e32 v247, v246
	s_nop 1
	v_permlane16_swap_b32 v247, v246
	s_nop 1
	v_add_f32_e32 v246, v246, v247
	s_mov_b64 exec, s[40:41]
	ds_write_b32 v248, v246 offset:35072
	s_mov_b64 exec, -1
	v_pk_mul_f32 v[244:245], v[36:37], v[36:37]
	v_pk_fma_f32 v[244:245], v[38:39], v[38:39], v[244:245]
	v_pk_fma_f32 v[244:245], v[32:33], v[32:33], v[244:245]
	v_pk_fma_f32 v[244:245], v[34:35], v[34:35], v[244:245]
	v_add_f32_e32 v246, v244, v245
	v_mul_f32_e32 v246, v246, v250
	v_mov_b32_e32 v247, v246
	s_nop 1
	v_permlane32_swap_b32 v247, v246
	s_nop 1
	v_add_f32_e32 v246, v246, v247
	v_mov_b32_e32 v247, v246
	s_nop 1
	v_permlane16_swap_b32 v247, v246
	s_nop 1
	v_add_f32_e32 v246, v246, v247
	s_mov_b64 exec, s[40:41]
	ds_write_b32 v248, v246 offset:35080
	s_mov_b64 exec, -1
	v_mul_f32_e32 v250, v210, v210
	v_pk_mul_f32 v[244:245], v[28:29], v[28:29]
	v_pk_fma_f32 v[244:245], v[30:31], v[30:31], v[244:245]
	v_pk_fma_f32 v[244:245], v[24:25], v[24:25], v[244:245]
	v_pk_fma_f32 v[244:245], v[26:27], v[26:27], v[244:245]
	v_add_f32_e32 v246, v244, v245
	v_mul_f32_e32 v246, v246, v250
	v_mov_b32_e32 v247, v246
	s_nop 1
	v_permlane32_swap_b32 v247, v246
	s_nop 1
	v_add_f32_e32 v246, v246, v247
	v_mov_b32_e32 v247, v246
	s_nop 1
	v_permlane16_swap_b32 v247, v246
	s_nop 1
	v_add_f32_e32 v246, v246, v247
	s_mov_b64 exec, s[40:41]
	ds_write_b32 v248, v246 offset:35328
	s_mov_b64 exec, -1
	v_pk_mul_f32 v[244:245], v[20:21], v[20:21]
	v_pk_fma_f32 v[244:245], v[22:23], v[22:23], v[244:245]
	v_pk_fma_f32 v[244:245], v[16:17], v[16:17], v[244:245]
	v_pk_fma_f32 v[244:245], v[18:19], v[18:19], v[244:245]
	v_add_f32_e32 v246, v244, v245
	v_mul_f32_e32 v246, v246, v250
	v_mov_b32_e32 v247, v246
	s_nop 1
	v_permlane32_swap_b32 v247, v246
	s_nop 1
	v_add_f32_e32 v246, v246, v247
	v_mov_b32_e32 v247, v246
	s_nop 1
	v_permlane16_swap_b32 v247, v246
	s_nop 1
	v_add_f32_e32 v246, v246, v247
	s_mov_b64 exec, s[40:41]
	ds_write_b32 v248, v246 offset:35336
	s_mov_b64 exec, -1
	v_mul_f32_e32 v250, v211, v211
	v_pk_mul_f32 v[244:245], v[12:13], v[12:13]
	v_pk_fma_f32 v[244:245], v[14:15], v[14:15], v[244:245]
	v_pk_fma_f32 v[244:245], v[8:9], v[8:9], v[244:245]
	v_pk_fma_f32 v[244:245], v[10:11], v[10:11], v[244:245]
	v_add_f32_e32 v246, v244, v245
	v_mul_f32_e32 v246, v246, v250
	v_mov_b32_e32 v247, v246
	s_nop 1
	v_permlane32_swap_b32 v247, v246
	s_nop 1
	v_add_f32_e32 v246, v246, v247
	v_mov_b32_e32 v247, v246
	s_nop 1
	v_permlane16_swap_b32 v247, v246
	s_nop 1
	v_add_f32_e32 v246, v246, v247
	s_mov_b64 exec, s[40:41]
	ds_write_b32 v248, v246 offset:35584
	s_mov_b64 exec, -1
	v_pk_mul_f32 v[244:245], v[4:5], v[4:5]
	v_pk_fma_f32 v[244:245], v[6:7], v[6:7], v[244:245]
	v_pk_fma_f32 v[244:245], v[0:1], v[0:1], v[244:245]
	v_pk_fma_f32 v[244:245], v[2:3], v[2:3], v[244:245]
	v_add_f32_e32 v246, v244, v245
	v_mul_f32_e32 v246, v246, v250
	v_mov_b32_e32 v247, v246
	s_nop 1
	v_permlane32_swap_b32 v247, v246
	s_nop 1
	v_add_f32_e32 v246, v246, v247
	v_mov_b32_e32 v247, v246
	s_nop 1
	v_permlane16_swap_b32 v247, v246
	s_nop 1
	v_add_f32_e32 v246, v246, v247
	s_mov_b64 exec, s[40:41]
	ds_write_b32 v248, v246 offset:35592
	s_mov_b64 exec, -1
	s_lshl_b32 s10, s37, 6
	s_mov_b32 s11, 0
	v_lshl_add_u64 v[150:151], v[150:151], 0, s[10:11]
	s_mov_b64 s[10:11], 0xc0000
	s_nop 0
	v_lshl_add_u64 v[248:249], v[150:151], 0, s[10:11]
	s_waitcnt vmcnt(0)
.Lkv_bar:
	s_waitcnt lgkmcnt(0)
	s_barrier
	s_cmp_lt_u32 s37, 2
	s_cbranch_scc0 .Lkv_v
	ds_read_b64 v[212:213], v147 offset:32768
	ds_read_b64 v[214:215], v147 offset:32776
	ds_read_b64 v[216:217], v147 offset:33024
	ds_read_b64 v[218:219], v147 offset:33032
	ds_read_b64 v[220:221], v147 offset:33280
	ds_read_b64 v[222:223], v147 offset:33288
	ds_read_b64 v[224:225], v147 offset:33536
	ds_read_b64 v[226:227], v147 offset:33544
	ds_read_b64 v[228:229], v147 offset:34816
	ds_read_b64 v[230:231], v147 offset:34824
	ds_read_b64 v[232:233], v147 offset:35072
	ds_read_b64 v[234:235], v147 offset:35080
	ds_read_b64 v[236:237], v147 offset:35328
	ds_read_b64 v[238:239], v147 offset:35336
	ds_read_b64 v[240:241], v147 offset:35584
	ds_read_b64 v[242:243], v147 offset:35592
	s_waitcnt lgkmcnt(0)
	v_add_f32_e32 v244, v212, v213
	v_add_f32_e32 v244, v244, v132
	v_fmamk_f32 v244, v244, 0x3c2aaaab, v194
	v_rsq_f32_e32 v244, v244
	s_nop 0
	v_mul_f32_e32 v244, v244, v204
	v_pk_mul_f32 v[128:129], v[128:129], v[244:245] op_sel_hi:[1,0]
	v_pk_mul_f32 v[130:131], v[130:131], v[244:245] op_sel_hi:[1,0]
	v_pk_mul_f32 v[124:125], v[124:125], v[244:245] op_sel_hi:[1,0]
	v_pk_mul_f32 v[126:127], v[126:127], v[244:245] op_sel_hi:[1,0]
	v_cvt_pk_bf16_f32 v128, v128, v129
	v_cvt_pk_bf16_f32 v129, v130, v131
	v_cvt_pk_bf16_f32 v130, v124, v125
	v_cvt_pk_bf16_f32 v131, v126, v127
	global_store_dwordx4 v[150:151], v[128:131], off
	v_add_f32_e32 v244, v214, v215
	v_add_f32_e32 v244, v244, v132
	v_fmamk_f32 v244, v244, 0x3c2aaaab, v194
	v_rsq_f32_e32 v244, v244
	s_nop 0
	v_mul_f32_e32 v244, v244, v204
	v_pk_mul_f32 v[120:121], v[120:121], v[244:245] op_sel_hi:[1,0]
	v_pk_mul_f32 v[122:123], v[122:123], v[244:245] op_sel_hi:[1,0]
	v_pk_mul_f32 v[116:117], v[116:117], v[244:245] op_sel_hi:[1,0]
	v_pk_mul_f32 v[118:119], v[118:119], v[244:245] op_sel_hi:[1,0]
	v_cvt_pk_bf16_f32 v120, v120, v121
	v_cvt_pk_bf16_f32 v121, v122, v123
	v_cvt_pk_bf16_f32 v122, v116, v117
	v_cvt_pk_bf16_f32 v123, v118, v119
	global_store_dwordx4 v[248:249], v[120:123], off
	s_mov_b64 vcc, 0xc00
	s_nop 0
	v_lshl_add_u64 v[150:151], v[150:151], 0, vcc
	v_lshl_add_u64 v[248:249], v[248:249], 0, vcc
	v_add_f32_e32 v244, v216, v217
	v_add_f32_e32 v244, v244, v133
	v_fmamk_f32 v244, v244, 0x3c2aaaab, v194
	v_rsq_f32_e32 v244, v244
	s_nop 0
	v_mul_f32_e32 v244, v244, v205
	v_pk_mul_f32 v[112:113], v[112:113], v[244:245] op_sel_hi:[1,0]
	v_pk_mul_f32 v[114:115], v[114:115], v[244:245] op_sel_hi:[1,0]
	v_pk_mul_f32 v[108:109], v[108:109], v[244:245] op_sel_hi:[1,0]
	v_pk_mul_f32 v[110:111], v[110:111], v[244:245] op_sel_hi:[1,0]
	v_cvt_pk_bf16_f32 v112, v112, v113
	v_cvt_pk_bf16_f32 v113, v114, v115
	v_cvt_pk_bf16_f32 v114, v108, v109
	v_cvt_pk_bf16_f32 v115, v110, v111
	global_store_dwordx4 v[150:151], v[112:115], off
	v_add_f32_e32 v244, v218, v219
	v_add_f32_e32 v244, v244, v133
	v_fmamk_f32 v244, v244, 0x3c2aaaab, v194
	v_rsq_f32_e32 v244, v244
	s_nop 0
	v_mul_f32_e32 v244, v244, v205
	v_pk_mul_f32 v[104:105], v[104:105], v[244:245] op_sel_hi:[1,0]
	v_pk_mul_f32 v[106:107], v[106:107], v[244:245] op_sel_hi:[1,0]
	v_pk_mul_f32 v[100:101], v[100:101], v[244:245] op_sel_hi:[1,0]
	v_pk_mul_f32 v[102:103], v[102:103], v[244:245] op_sel_hi:[1,0]
	v_cvt_pk_bf16_f32 v104, v104, v105
	v_cvt_pk_bf16_f32 v105, v106, v107
	v_cvt_pk_bf16_f32 v106, v100, v101
	v_cvt_pk_bf16_f32 v107, v102, v103
	global_store_dwordx4 v[248:249], v[104:107], off
	s_mov_b64 vcc, 0xc00
	s_nop 0
	v_lshl_add_u64 v[150:151], v[150:151], 0, vcc
	v_lshl_add_u64 v[248:249], v[248:249], 0, vcc
	v_add_f32_e32 v244, v220, v221
	v_add_f32_e32 v244, v244, v134
	v_fmamk_f32 v244, v244, 0x3c2aaaab, v194
	v_rsq_f32_e32 v244, v244
	s_nop 0
	v_mul_f32_e32 v244, v244, v206
	v_pk_mul_f32 v[96:97], v[96:97], v[244:245] op_sel_hi:[1,0]
	v_pk_mul_f32 v[98:99], v[98:99], v[244:245] op_sel_hi:[1,0]
	v_pk_mul_f32 v[92:93], v[92:93], v[244:245] op_sel_hi:[1,0]
	v_pk_mul_f32 v[94:95], v[94:95], v[244:245] op_sel_hi:[1,0]
	v_cvt_pk_bf16_f32 v96, v96, v97
	v_cvt_pk_bf16_f32 v97, v98, v99
	v_cvt_pk_bf16_f32 v98, v92, v93
	v_cvt_pk_bf16_f32 v99, v94, v95
	global_store_dwordx4 v[150:151], v[96:99], off
	v_add_f32_e32 v244, v222, v223
	v_add_f32_e32 v244, v244, v134
	v_fmamk_f32 v244, v244, 0x3c2aaaab, v194
	v_rsq_f32_e32 v244, v244
	s_nop 0
	v_mul_f32_e32 v244, v244, v206
	v_pk_mul_f32 v[88:89], v[88:89], v[244:245] op_sel_hi:[1,0]
	v_pk_mul_f32 v[90:91], v[90:91], v[244:245] op_sel_hi:[1,0]
	v_pk_mul_f32 v[84:85], v[84:85], v[244:245] op_sel_hi:[1,0]
	v_pk_mul_f32 v[86:87], v[86:87], v[244:245] op_sel_hi:[1,0]
	v_cvt_pk_bf16_f32 v88, v88, v89
	v_cvt_pk_bf16_f32 v89, v90, v91
	v_cvt_pk_bf16_f32 v90, v84, v85
	v_cvt_pk_bf16_f32 v91, v86, v87
	global_store_dwordx4 v[248:249], v[88:91], off
	s_mov_b64 vcc, 0xc00
	s_nop 0
	v_lshl_add_u64 v[150:151], v[150:151], 0, vcc
	v_lshl_add_u64 v[248:249], v[248:249], 0, vcc
	v_add_f32_e32 v244, v224, v225
	v_add_f32_e32 v244, v244, v135
	v_fmamk_f32 v244, v244, 0x3c2aaaab, v194
	v_rsq_f32_e32 v244, v244
	s_nop 0
	v_mul_f32_e32 v244, v244, v207
	v_pk_mul_f32 v[76:77], v[76:77], v[244:245] op_sel_hi:[1,0]
	v_pk_mul_f32 v[78:79], v[78:79], v[244:245] op_sel_hi:[1,0]
	v_pk_mul_f32 v[72:73], v[72:73], v[244:245] op_sel_hi:[1,0]
	v_pk_mul_f32 v[74:75], v[74:75], v[244:245] op_sel_hi:[1,0]
	v_cvt_pk_bf16_f32 v76, v76, v77
	v_cvt_pk_bf16_f32 v77, v78, v79
	v_cvt_pk_bf16_f32 v78, v72, v73
	v_cvt_pk_bf16_f32 v79, v74, v75
	global_store_dwordx4 v[150:151], v[76:79], off
	v_add_f32_e32 v244, v226, v227
	v_add_f32_e32 v244, v244, v135
	v_fmamk_f32 v244, v244, 0x3c2aaaab, v194
	v_rsq_f32_e32 v244, v244
	s_nop 0
	v_mul_f32_e32 v244, v244, v207
	v_pk_mul_f32 v[68:69], v[68:69], v[244:245] op_sel_hi:[1,0]
	v_pk_mul_f32 v[70:71], v[70:71], v[244:245] op_sel_hi:[1,0]
	v_pk_mul_f32 v[64:65], v[64:65], v[244:245] op_sel_hi:[1,0]
	v_pk_mul_f32 v[66:67], v[66:67], v[244:245] op_sel_hi:[1,0]
	v_cvt_pk_bf16_f32 v68, v68, v69
	v_cvt_pk_bf16_f32 v69, v70, v71
	v_cvt_pk_bf16_f32 v70, v64, v65
	v_cvt_pk_bf16_f32 v71, v66, v67
	global_store_dwordx4 v[248:249], v[68:71], off
	s_mov_b64 vcc, 0x3c00
	s_nop 0
	v_lshl_add_u64 v[150:151], v[150:151], 0, vcc
	v_lshl_add_u64 v[248:249], v[248:249], 0, vcc
	v_add_f32_e32 v244, v228, v229
	v_add_f32_e32 v244, v244, v136
	v_fmamk_f32 v244, v244, 0x3c2aaaab, v194
	v_rsq_f32_e32 v244, v244
	s_nop 0
	v_mul_f32_e32 v244, v244, v208
	v_pk_mul_f32 v[60:61], v[60:61], v[244:245] op_sel_hi:[1,0]
	v_pk_mul_f32 v[62:63], v[62:63], v[244:245] op_sel_hi:[1,0]
	v_pk_mul_f32 v[56:57], v[56:57], v[244:245] op_sel_hi:[1,0]
	v_pk_mul_f32 v[58:59], v[58:59], v[244:245] op_sel_hi:[1,0]
	v_cvt_pk_bf16_f32 v60, v60, v61
	v_cvt_pk_bf16_f32 v61, v62, v63
	v_cvt_pk_bf16_f32 v62, v56, v57
	v_cvt_pk_bf16_f32 v63, v58, v59
	global_store_dwordx4 v[150:151], v[60:63], off
	v_add_f32_e32 v244, v230, v231
	v_add_f32_e32 v244, v244, v136
	v_fmamk_f32 v244, v244, 0x3c2aaaab, v194
	v_rsq_f32_e32 v244, v244
	s_nop 0
	v_mul_f32_e32 v244, v244, v208
	v_pk_mul_f32 v[52:53], v[52:53], v[244:245] op_sel_hi:[1,0]
	v_pk_mul_f32 v[54:55], v[54:55], v[244:245] op_sel_hi:[1,0]
	v_pk_mul_f32 v[48:49], v[48:49], v[244:245] op_sel_hi:[1,0]
	v_pk_mul_f32 v[50:51], v[50:51], v[244:245] op_sel_hi:[1,0]
	v_cvt_pk_bf16_f32 v52, v52, v53
	v_cvt_pk_bf16_f32 v53, v54, v55
	v_cvt_pk_bf16_f32 v54, v48, v49
	v_cvt_pk_bf16_f32 v55, v50, v51
	global_store_dwordx4 v[248:249], v[52:55], off
	s_mov_b64 vcc, 0xc00
	s_nop 0
	v_lshl_add_u64 v[150:151], v[150:151], 0, vcc
	v_lshl_add_u64 v[248:249], v[248:249], 0, vcc
	v_add_f32_e32 v244, v232, v233
	v_add_f32_e32 v244, v244, v137
	v_fmamk_f32 v244, v244, 0x3c2aaaab, v194
	v_rsq_f32_e32 v244, v244
	s_nop 0
	v_mul_f32_e32 v244, v244, v209
	v_pk_mul_f32 v[44:45], v[44:45], v[244:245] op_sel_hi:[1,0]
	v_pk_mul_f32 v[46:47], v[46:47], v[244:245] op_sel_hi:[1,0]
	v_pk_mul_f32 v[40:41], v[40:41], v[244:245] op_sel_hi:[1,0]
	v_pk_mul_f32 v[42:43], v[42:43], v[244:245] op_sel_hi:[1,0]
	v_cvt_pk_bf16_f32 v44, v44, v45
	v_cvt_pk_bf16_f32 v45, v46, v47
	v_cvt_pk_bf16_f32 v46, v40, v41
	v_cvt_pk_bf16_f32 v47, v42, v43
	global_store_dwordx4 v[150:151], v[44:47], off
	v_add_f32_e32 v244, v234, v235
	v_add_f32_e32 v244, v244, v137
	v_fmamk_f32 v244, v244, 0x3c2aaaab, v194
	v_rsq_f32_e32 v244, v244
	s_nop 0
	v_mul_f32_e32 v244, v244, v209
	v_pk_mul_f32 v[36:37], v[36:37], v[244:245] op_sel_hi:[1,0]
	v_pk_mul_f32 v[38:39], v[38:39], v[244:245] op_sel_hi:[1,0]
	v_pk_mul_f32 v[32:33], v[32:33], v[244:245] op_sel_hi:[1,0]
	v_pk_mul_f32 v[34:35], v[34:35], v[244:245] op_sel_hi:[1,0]
	v_cvt_pk_bf16_f32 v36, v36, v37
	v_cvt_pk_bf16_f32 v37, v38, v39
	v_cvt_pk_bf16_f32 v38, v32, v33
	v_cvt_pk_bf16_f32 v39, v34, v35
	global_store_dwordx4 v[248:249], v[36:39], off
	s_mov_b64 vcc, 0xc00
	s_nop 0
	v_lshl_add_u64 v[150:151], v[150:151], 0, vcc
	v_lshl_add_u64 v[248:249], v[248:249], 0, vcc
	v_add_f32_e32 v244, v236, v237
	v_add_f32_e32 v244, v244, v138
	v_fmamk_f32 v244, v244, 0x3c2aaaab, v194
	v_rsq_f32_e32 v244, v244
	s_nop 0
	v_mul_f32_e32 v244, v244, v210
	v_pk_mul_f32 v[28:29], v[28:29], v[244:245] op_sel_hi:[1,0]
	v_pk_mul_f32 v[30:31], v[30:31], v[244:245] op_sel_hi:[1,0]
	v_pk_mul_f32 v[24:25], v[24:25], v[244:245] op_sel_hi:[1,0]
	v_pk_mul_f32 v[26:27], v[26:27], v[244:245] op_sel_hi:[1,0]
	v_cvt_pk_bf16_f32 v28, v28, v29
	v_cvt_pk_bf16_f32 v29, v30, v31
	v_cvt_pk_bf16_f32 v30, v24, v25
	v_cvt_pk_bf16_f32 v31, v26, v27
	global_store_dwordx4 v[150:151], v[28:31], off
	v_add_f32_e32 v244, v238, v239
	v_add_f32_e32 v244, v244, v138
	v_fmamk_f32 v244, v244, 0x3c2aaaab, v194
	v_rsq_f32_e32 v244, v244
	s_nop 0
	v_mul_f32_e32 v244, v244, v210
	v_pk_mul_f32 v[20:21], v[20:21], v[244:245] op_sel_hi:[1,0]
	v_pk_mul_f32 v[22:23], v[22:23], v[244:245] op_sel_hi:[1,0]
	v_pk_mul_f32 v[16:17], v[16:17], v[244:245] op_sel_hi:[1,0]
	v_pk_mul_f32 v[18:19], v[18:19], v[244:245] op_sel_hi:[1,0]
	v_cvt_pk_bf16_f32 v20, v20, v21
	v_cvt_pk_bf16_f32 v21, v22, v23
	v_cvt_pk_bf16_f32 v22, v16, v17
	v_cvt_pk_bf16_f32 v23, v18, v19
	global_store_dwordx4 v[248:249], v[20:23], off
	s_mov_b64 vcc, 0xc00
	s_nop 0
	v_lshl_add_u64 v[150:151], v[150:151], 0, vcc
	v_lshl_add_u64 v[248:249], v[248:249], 0, vcc
	v_add_f32_e32 v244, v240, v241
	v_add_f32_e32 v244, v244, v139
	v_fmamk_f32 v244, v244, 0x3c2aaaab, v194
	v_rsq_f32_e32 v244, v244
	s_nop 0
	v_mul_f32_e32 v244, v244, v211
	v_pk_mul_f32 v[12:13], v[12:13], v[244:245] op_sel_hi:[1,0]
	v_pk_mul_f32 v[14:15], v[14:15], v[244:245] op_sel_hi:[1,0]
	v_pk_mul_f32 v[8:9], v[8:9], v[244:245] op_sel_hi:[1,0]
	v_pk_mul_f32 v[10:11], v[10:11], v[244:245] op_sel_hi:[1,0]
	v_cvt_pk_bf16_f32 v12, v12, v13
	v_cvt_pk_bf16_f32 v13, v14, v15
	v_cvt_pk_bf16_f32 v14, v8, v9
	v_cvt_pk_bf16_f32 v15, v10, v11
	global_store_dwordx4 v[150:151], v[12:15], off
	v_add_f32_e32 v244, v242, v243
	v_add_f32_e32 v244, v244, v139
	v_fmamk_f32 v244, v244, 0x3c2aaaab, v194
	v_rsq_f32_e32 v244, v244
	s_nop 0
	v_mul_f32_e32 v244, v244, v211
	v_pk_mul_f32 v[4:5], v[4:5], v[244:245] op_sel_hi:[1,0]
	v_pk_mul_f32 v[6:7], v[6:7], v[244:245] op_sel_hi:[1,0]
	v_pk_mul_f32 v[0:1], v[0:1], v[244:245] op_sel_hi:[1,0]
	v_pk_mul_f32 v[2:3], v[2:3], v[244:245] op_sel_hi:[1,0]
	v_cvt_pk_bf16_f32 v4, v4, v5
	v_cvt_pk_bf16_f32 v5, v6, v7
	v_cvt_pk_bf16_f32 v6, v0, v1
	v_cvt_pk_bf16_f32 v7, v2, v3
	global_store_dwordx4 v[248:249], v[4:7], off
	s_branch .Lkv_end
.Lkv_v:
	ds_read_b64 v[212:213], v147 offset:32768
	ds_read_b64 v[214:215], v147 offset:33024
	ds_read_b64 v[216:217], v147 offset:33280
	ds_read_b64 v[218:219], v147 offset:33536
	ds_read_b64 v[220:221], v147 offset:34816
	ds_read_b64 v[222:223], v147 offset:35072
	ds_read_b64 v[224:225], v147 offset:35328
	ds_read_b64 v[226:227], v147 offset:35584
	s_waitcnt lgkmcnt(0)
	v_add_f32_e32 v244, v212, v213
	v_add_f32_e32 v244, v244, v132
	v_fmamk_f32 v244, v244, 0x3c2aaaab, v194
	v_rsq_f32_e32 v244, v244
	v_lshlrev_b32_e32 v82, 16, v160
	v_and_b32_e32 v160, 0xffff0000, v160
	v_lshlrev_b32_e32 v83, 16, v161
	v_and_b32_e32 v161, 0xffff0000, v161
	v_lshlrev_b32_e32 v246, 16, v162
	v_and_b32_e32 v162, 0xffff0000, v162
	v_lshlrev_b32_e32 v247, 16, v163
	v_and_b32_e32 v163, 0xffff0000, v163
	v_mul_f32_e32 v82, v82, v244
	v_mul_f32_e32 v160, v160, v244
	v_mul_f32_e32 v83, v83, v244
	v_mul_f32_e32 v161, v161, v244
	v_mul_f32_e32 v246, v246, v244
	v_mul_f32_e32 v162, v162, v244
	v_mul_f32_e32 v247, v247, v244
	v_mul_f32_e32 v163, v163, v244
	v_cvt_pk_bf16_f32 v160, v82, v160
	v_cvt_pk_bf16_f32 v161, v83, v161
	v_cvt_pk_bf16_f32 v162, v246, v162
	v_cvt_pk_bf16_f32 v163, v247, v163
	global_store_dwordx4 v[150:151], v[160:163], off
	s_mov_b64 vcc, 0xc00
	s_nop 0
	v_lshl_add_u64 v[150:151], v[150:151], 0, vcc
	v_add_f32_e32 v244, v214, v215
	v_add_f32_e32 v244, v244, v133
	v_fmamk_f32 v244, v244, 0x3c2aaaab, v194
	v_rsq_f32_e32 v244, v244
	v_lshlrev_b32_e32 v82, 16, v164
	v_and_b32_e32 v164, 0xffff0000, v164
	v_lshlrev_b32_e32 v83, 16, v165
	v_and_b32_e32 v165, 0xffff0000, v165
	v_lshlrev_b32_e32 v246, 16, v166
	v_and_b32_e32 v166, 0xffff0000, v166
	v_lshlrev_b32_e32 v247, 16, v167
	v_and_b32_e32 v167, 0xffff0000, v167
	v_mul_f32_e32 v82, v82, v244
	v_mul_f32_e32 v164, v164, v244
	v_mul_f32_e32 v83, v83, v244
	v_mul_f32_e32 v165, v165, v244
	v_mul_f32_e32 v246, v246, v244
	v_mul_f32_e32 v166, v166, v244
	v_mul_f32_e32 v247, v247, v244
	v_mul_f32_e32 v167, v167, v244
	v_cvt_pk_bf16_f32 v164, v82, v164
	v_cvt_pk_bf16_f32 v165, v83, v165
	v_cvt_pk_bf16_f32 v166, v246, v166
	v_cvt_pk_bf16_f32 v167, v247, v167
	global_store_dwordx4 v[150:151], v[164:167], off
	s_mov_b64 vcc, 0xc00
	s_nop 0
	v_lshl_add_u64 v[150:151], v[150:151], 0, vcc
	v_add_f32_e32 v244, v216, v217
	v_add_f32_e32 v244, v244, v134
	v_fmamk_f32 v244, v244, 0x3c2aaaab, v194
	v_rsq_f32_e32 v244, v244
	v_lshlrev_b32_e32 v82, 16, v168
	v_and_b32_e32 v168, 0xffff0000, v168
	v_lshlrev_b32_e32 v83, 16, v169
	v_and_b32_e32 v169, 0xffff0000, v169
	v_lshlrev_b32_e32 v246, 16, v170
	v_and_b32_e32 v170, 0xffff0000, v170
	v_lshlrev_b32_e32 v247, 16, v171
	v_and_b32_e32 v171, 0xffff0000, v171
	v_mul_f32_e32 v82, v82, v244
	v_mul_f32_e32 v168, v168, v244
	v_mul_f32_e32 v83, v83, v244
	v_mul_f32_e32 v169, v169, v244
	v_mul_f32_e32 v246, v246, v244
	v_mul_f32_e32 v170, v170, v244
	v_mul_f32_e32 v247, v247, v244
	v_mul_f32_e32 v171, v171, v244
	v_cvt_pk_bf16_f32 v168, v82, v168
	v_cvt_pk_bf16_f32 v169, v83, v169
	v_cvt_pk_bf16_f32 v170, v246, v170
	v_cvt_pk_bf16_f32 v171, v247, v171
	global_store_dwordx4 v[150:151], v[168:171], off
	s_mov_b64 vcc, 0xc00
	s_nop 0
	v_lshl_add_u64 v[150:151], v[150:151], 0, vcc
	v_add_f32_e32 v244, v218, v219
	v_add_f32_e32 v244, v244, v135
	v_fmamk_f32 v244, v244, 0x3c2aaaab, v194
	v_rsq_f32_e32 v244, v244
	v_lshlrev_b32_e32 v82, 16, v172
	v_and_b32_e32 v172, 0xffff0000, v172
	v_lshlrev_b32_e32 v83, 16, v173
	v_and_b32_e32 v173, 0xffff0000, v173
	v_lshlrev_b32_e32 v246, 16, v174
	v_and_b32_e32 v174, 0xffff0000, v174
	v_lshlrev_b32_e32 v247, 16, v175
	v_and_b32_e32 v175, 0xffff0000, v175
	v_mul_f32_e32 v82, v82, v244
	v_mul_f32_e32 v172, v172, v244
	v_mul_f32_e32 v83, v83, v244
	v_mul_f32_e32 v173, v173, v244
	v_mul_f32_e32 v246, v246, v244
	v_mul_f32_e32 v174, v174, v244
	v_mul_f32_e32 v247, v247, v244
	v_mul_f32_e32 v175, v175, v244
	v_cvt_pk_bf16_f32 v172, v82, v172
	v_cvt_pk_bf16_f32 v173, v83, v173
	v_cvt_pk_bf16_f32 v174, v246, v174
	v_cvt_pk_bf16_f32 v175, v247, v175
	global_store_dwordx4 v[150:151], v[172:175], off
	s_mov_b64 vcc, 0x3c00
	s_nop 0
	v_lshl_add_u64 v[150:151], v[150:151], 0, vcc
	v_add_f32_e32 v244, v220, v221
	v_add_f32_e32 v244, v244, v136
	v_fmamk_f32 v244, v244, 0x3c2aaaab, v194
	v_rsq_f32_e32 v244, v244
	v_lshlrev_b32_e32 v82, 16, v176
	v_and_b32_e32 v176, 0xffff0000, v176
	v_lshlrev_b32_e32 v83, 16, v177
	v_and_b32_e32 v177, 0xffff0000, v177
	v_lshlrev_b32_e32 v246, 16, v178
	v_and_b32_e32 v178, 0xffff0000, v178
	v_lshlrev_b32_e32 v247, 16, v179
	v_and_b32_e32 v179, 0xffff0000, v179
	v_mul_f32_e32 v82, v82, v244
	v_mul_f32_e32 v176, v176, v244
	v_mul_f32_e32 v83, v83, v244
	v_mul_f32_e32 v177, v177, v244
	v_mul_f32_e32 v246, v246, v244
	v_mul_f32_e32 v178, v178, v244
	v_mul_f32_e32 v247, v247, v244
	v_mul_f32_e32 v179, v179, v244
	v_cvt_pk_bf16_f32 v176, v82, v176
	v_cvt_pk_bf16_f32 v177, v83, v177
	v_cvt_pk_bf16_f32 v178, v246, v178
	v_cvt_pk_bf16_f32 v179, v247, v179
	global_store_dwordx4 v[150:151], v[176:179], off
	s_mov_b64 vcc, 0xc00
	s_nop 0
	v_lshl_add_u64 v[150:151], v[150:151], 0, vcc
	v_add_f32_e32 v244, v222, v223
	v_add_f32_e32 v244, v244, v137
	v_fmamk_f32 v244, v244, 0x3c2aaaab, v194
	v_rsq_f32_e32 v244, v244
	v_lshlrev_b32_e32 v82, 16, v180
	v_and_b32_e32 v180, 0xffff0000, v180
	v_lshlrev_b32_e32 v83, 16, v181
	v_and_b32_e32 v181, 0xffff0000, v181
	v_lshlrev_b32_e32 v246, 16, v182
	v_and_b32_e32 v182, 0xffff0000, v182
	v_lshlrev_b32_e32 v247, 16, v183
	v_and_b32_e32 v183, 0xffff0000, v183
	v_mul_f32_e32 v82, v82, v244
	v_mul_f32_e32 v180, v180, v244
	v_mul_f32_e32 v83, v83, v244
	v_mul_f32_e32 v181, v181, v244
	v_mul_f32_e32 v246, v246, v244
	v_mul_f32_e32 v182, v182, v244
	v_mul_f32_e32 v247, v247, v244
	v_mul_f32_e32 v183, v183, v244
	v_cvt_pk_bf16_f32 v180, v82, v180
	v_cvt_pk_bf16_f32 v181, v83, v181
	v_cvt_pk_bf16_f32 v182, v246, v182
	v_cvt_pk_bf16_f32 v183, v247, v183
	global_store_dwordx4 v[150:151], v[180:183], off
	s_mov_b64 vcc, 0xc00
	s_nop 0
	v_lshl_add_u64 v[150:151], v[150:151], 0, vcc
	v_add_f32_e32 v244, v224, v225
	v_add_f32_e32 v244, v244, v138
	v_fmamk_f32 v244, v244, 0x3c2aaaab, v194
	v_rsq_f32_e32 v244, v244
	v_lshlrev_b32_e32 v82, 16, v184
	v_and_b32_e32 v184, 0xffff0000, v184
	v_lshlrev_b32_e32 v83, 16, v185
	v_and_b32_e32 v185, 0xffff0000, v185
	v_lshlrev_b32_e32 v246, 16, v186
	v_and_b32_e32 v186, 0xffff0000, v186
	v_lshlrev_b32_e32 v247, 16, v187
	v_and_b32_e32 v187, 0xffff0000, v187
	v_mul_f32_e32 v82, v82, v244
	v_mul_f32_e32 v184, v184, v244
	v_mul_f32_e32 v83, v83, v244
	v_mul_f32_e32 v185, v185, v244
	v_mul_f32_e32 v246, v246, v244
	v_mul_f32_e32 v186, v186, v244
	v_mul_f32_e32 v247, v247, v244
	v_mul_f32_e32 v187, v187, v244
	v_cvt_pk_bf16_f32 v184, v82, v184
	v_cvt_pk_bf16_f32 v185, v83, v185
	v_cvt_pk_bf16_f32 v186, v246, v186
	v_cvt_pk_bf16_f32 v187, v247, v187
	global_store_dwordx4 v[150:151], v[184:187], off
	s_mov_b64 vcc, 0xc00
	s_nop 0
	v_lshl_add_u64 v[150:151], v[150:151], 0, vcc
	v_add_f32_e32 v244, v226, v227
	v_add_f32_e32 v244, v244, v139
	v_fmamk_f32 v244, v244, 0x3c2aaaab, v194
	v_rsq_f32_e32 v244, v244
	v_lshlrev_b32_e32 v82, 16, v188
	v_and_b32_e32 v188, 0xffff0000, v188
	v_lshlrev_b32_e32 v83, 16, v189
	v_and_b32_e32 v189, 0xffff0000, v189
	v_lshlrev_b32_e32 v246, 16, v190
	v_and_b32_e32 v190, 0xffff0000, v190
	v_lshlrev_b32_e32 v247, 16, v191
	v_and_b32_e32 v191, 0xffff0000, v191
	v_mul_f32_e32 v82, v82, v244
	v_mul_f32_e32 v188, v188, v244
	v_mul_f32_e32 v83, v83, v244
	v_mul_f32_e32 v189, v189, v244
	v_mul_f32_e32 v246, v246, v244
	v_mul_f32_e32 v190, v190, v244
	v_mul_f32_e32 v247, v247, v244
	v_mul_f32_e32 v191, v191, v244
	v_cvt_pk_bf16_f32 v188, v82, v188
	v_cvt_pk_bf16_f32 v189, v83, v189
	v_cvt_pk_bf16_f32 v190, v246, v190
	v_cvt_pk_bf16_f32 v191, v247, v191
	global_store_dwordx4 v[150:151], v[188:191], off
